# e1 A-wave QK reads pipelined + e4 B-wave LDS reads under DMA issue + e6 sample-attn Q hoisted out of tile loop
# baseline (speedup 1.0000x reference)
; __device__ __forceinline__ void attn_sample_unit(int b, int h, int split, const bf16* __restrict__ Q, const float* __restrict__ cache_k, const float* __restrict__ cache_v, ...
;     ...
;     const int c = wid & 1, vh = wid >> 1;
;     float* li_l = scr + wid * 64; float* al_l = li_l + 32;
;     float m_reg = -1e30f, l_reg = 0; f32x16 o[4] = {};
;     const bf16* Qw = Q + (size_t)(MP + b * 16 + (r32 & 15)) * LD + h * 256 + c * 128 + hi * 8;
;     __syncthreads();
;     for (int j = 0; j < nT; ++j) {
;       char* bb = lds + (j & 1) * 65536;
;       f32x16 p0, p1; float mn, al; bf16x8 pa0, pa1, pa2, pa3; bf16x8 qr[8];
;       asm volatile("" : "+v"(Qw));
; #pragma unroll
;       for (int d0 = 0; d0 < 8; ++d0) { bf16x8 v = *reinterpret_cast<const bf16x8*>(Qw + d0 * 16); if (r32 >= 16) v = (bf16x8){0, 0, 0, 0, 0, 0, 0, 0}; qr[d0] = v; }
.LBB0_355:
	v_mov_b32_e32 v104, v0
	s_bfe_u32 s5, s48, 0x30001
	s_and_b32 s64, s48, 1
	v_readfirstlane_b32 s37, v104
	s_lshl_b32 s4, s5, 8
	s_ashr_i32 s36, s37, 6
	v_and_b32_e32 v132, 63, v104
	v_and_b32_e32 v106, 31, v104
	v_bfe_u32 v107, v104, 5, 1
	s_mov_b64 s[18:19], -1
	s_cmp_lt_i32 s36, 4
	v_cndmask_b32_e64 v101, 0, 1, s[2:3]
	v_lshlrev_b32_e32 v105, 3, v132
	v_lshlrev_b32_e32 v100, 4, v132
	s_cbranch_scc0 .LBB0_368
	s_and_b32 s8, s37, 0x3fffffc0
	s_lshl_b32 s8, s8, 2
	s_and_b32 s66, s48, -16
	s_add_i32 s67, s8, 0
	s_add_i32 s8, s66, 0x4000
	v_and_or_b32 v4, v104, 15, s8
	v_readfirstlane_b32 s7, v101
	v_ashrrev_i32_e32 v5, 31, v4
	s_lshl_b32 s6, s7, 11
	s_lshl_b32 s21, s7, 16
	s_lshl_b32 s7, s4, 2
	v_lshlrev_b64 v[4:5], 12, v[4:5]
	s_add_i32 s65, s7, 0
	s_bfe_u32 s7, s37, 0x10006
	v_lshl_add_u64 v[4:5], s[0:1], 0, v[4:5]
	s_lshl_b32 s10, s4, 1
	v_lshl_add_u64 v[4:5], v[4:5], 0, s[10:11]
	s_lshl_b32 s10, s7, 8
	v_lshl_add_u64 v[4:5], v[4:5], 0, s[10:11]
	v_lshlrev_b32_e32 v2, 4, v107
	v_lshl_add_u64 v[102:103], v[4:5], 0, v[2:3]
	flat_load_dwordx4 v[208:211], v[102:103]
	flat_load_dwordx4 v[212:215], v[102:103] offset:32
	flat_load_dwordx4 v[216:219], v[102:103] offset:64
	flat_load_dwordx4 v[220:223], v[102:103] offset:96
	flat_load_dwordx4 v[224:227], v[102:103] offset:128
	flat_load_dwordx4 v[228:231], v[102:103] offset:160
	flat_load_dwordx4 v[232:235], v[102:103] offset:192
	flat_load_dwordx4 v[236:239], v[102:103] offset:224
	v_lshlrev_b32_e32 v4, 4, v106
	s_movk_i32 s8, 0x70
	v_and_b32_e32 v5, 0x70, v4
	v_bitop3_b32 v109, v2, v4, s8 bitop3:0x78
	s_movk_i32 s8, 0xa0
	v_bitop3_b32 v114, v2, v5, s8 bitop3:0x36
	s_movk_i32 s8, 0xe0
	v_bitop3_b32 v110, v2, v5, 32 bitop3:0x36
	v_bitop3_b32 v111, v2, v5, 64 bitop3:0x36
	v_bitop3_b32 v112, v2, v5, s22 bitop3:0x36
	v_bitop3_b32 v113, v2, v5, s70 bitop3:0x36
	v_bitop3_b32 v115, v2, v5, s34 bitop3:0x36
	v_bitop3_b32 v116, v2, v5, s8 bitop3:0x36
	v_and_b32_e32 v4, 0xc0, v100
	v_lshlrev_b32_e32 v5, 1, v132
	v_and_or_b32 v4, v105, 24, v4
	v_and_b32_e32 v5, 32, v5
	v_and_b32_e32 v6, 0x100, v105
	v_mov_b32_e32 v18, v3
	v_mov_b32_e32 v19, v3
	s_ashr_i32 s20, s37, 7
	s_add_i32 s67, s67, 0x22000
	v_or3_b32 v119, v4, v5, v6
	v_mov_b32_e32 v4, v3
	v_mov_b32_e32 v5, v3
	v_mov_b32_e32 v6, v3
	v_mov_b32_e32 v7, v3
	v_mov_b32_e32 v8, v3
	v_mov_b32_e32 v9, v3
	v_mov_b32_e32 v10, v3
	v_mov_b32_e32 v11, v3
	v_mov_b32_e32 v12, v3
	v_mov_b32_e32 v13, v3
	v_mov_b32_e32 v14, v3
	v_mov_b32_e32 v15, v3
	v_mov_b32_e32 v16, v3
	v_mov_b32_e32 v17, v3
	v_mov_b64_e32 v[34:35], v[18:19]
	v_mov_b64_e32 v[50:51], v[18:19]
	v_mov_b64_e32 v[66:67], v[18:19]
	s_bitset1_b32 s21, 21
	s_add_i32 s65, s65, 0x20000
	v_cmp_lt_u32_e64 s[40:41], 15, v106
	s_lshl_b32 s10, s7, 14
	v_lshlrev_b32_e32 v108, 8, v106
	v_cmp_gt_u32_e64 s[38:39], 32, v132
	v_lshl_add_u32 v117, v106, 2, s67
	s_lshl_b32 s70, s20, 14
	s_mov_b32 s71, 0
	v_mov_b32_e32 v120, 0
	v_mov_b32_e32 v118, 0xf149f2ca
	v_mov_b64_e32 v[32:33], v[16:17]
	v_mov_b64_e32 v[30:31], v[14:15]
	v_mov_b64_e32 v[28:29], v[12:13]
	v_mov_b64_e32 v[26:27], v[10:11]
	v_mov_b64_e32 v[24:25], v[8:9]
	v_mov_b64_e32 v[22:23], v[6:7]
	v_mov_b64_e32 v[20:21], v[4:5]
	v_mov_b64_e32 v[48:49], v[16:17]
	v_mov_b64_e32 v[46:47], v[14:15]
	v_mov_b64_e32 v[44:45], v[12:13]
	v_mov_b64_e32 v[42:43], v[10:11]
	v_mov_b64_e32 v[40:41], v[8:9]
	v_mov_b64_e32 v[38:39], v[6:7]
	v_mov_b64_e32 v[36:37], v[4:5]
	v_mov_b64_e32 v[64:65], v[16:17]
	v_mov_b64_e32 v[62:63], v[14:15]
	v_mov_b64_e32 v[60:61], v[12:13]
	v_mov_b64_e32 v[58:59], v[10:11]
	v_mov_b64_e32 v[56:57], v[8:9]
	v_mov_b64_e32 v[54:55], v[6:7]
	v_mov_b64_e32 v[52:53], v[4:5]
	s_waitcnt vmcnt(0) lgkmcnt(0)
	v_cndmask_b32_e64 v208, v208, 0, s[40:41]
	v_cndmask_b32_e64 v209, v209, 0, s[40:41]
	v_cndmask_b32_e64 v210, v210, 0, s[40:41]
	v_cndmask_b32_e64 v211, v211, 0, s[40:41]
	v_cndmask_b32_e64 v212, v212, 0, s[40:41]
	v_cndmask_b32_e64 v213, v213, 0, s[40:41]
	v_cndmask_b32_e64 v214, v214, 0, s[40:41]
	v_cndmask_b32_e64 v215, v215, 0, s[40:41]
	v_cndmask_b32_e64 v216, v216, 0, s[40:41]
	v_cndmask_b32_e64 v217, v217, 0, s[40:41]
	v_cndmask_b32_e64 v218, v218, 0, s[40:41]
	v_cndmask_b32_e64 v219, v219, 0, s[40:41]
	v_cndmask_b32_e64 v220, v220, 0, s[40:41]
	v_cndmask_b32_e64 v221, v221, 0, s[40:41]
	v_cndmask_b32_e64 v222, v222, 0, s[40:41]
	v_cndmask_b32_e64 v223, v223, 0, s[40:41]
	v_cndmask_b32_e64 v224, v224, 0, s[40:41]
	v_cndmask_b32_e64 v225, v225, 0, s[40:41]
	v_cndmask_b32_e64 v226, v226, 0, s[40:41]
	v_cndmask_b32_e64 v227, v227, 0, s[40:41]
	v_cndmask_b32_e64 v228, v228, 0, s[40:41]
	v_cndmask_b32_e64 v229, v229, 0, s[40:41]
	v_cndmask_b32_e64 v230, v230, 0, s[40:41]
	v_cndmask_b32_e64 v231, v231, 0, s[40:41]
	v_cndmask_b32_e64 v232, v232, 0, s[40:41]
	v_cndmask_b32_e64 v233, v233, 0, s[40:41]
	v_cndmask_b32_e64 v234, v234, 0, s[40:41]
	v_cndmask_b32_e64 v235, v235, 0, s[40:41]
	v_cndmask_b32_e64 v236, v236, 0, s[40:41]
	v_cndmask_b32_e64 v237, v237, 0, s[40:41]
	v_cndmask_b32_e64 v238, v238, 0, s[40:41]
	v_cndmask_b32_e64 v239, v239, 0, s[40:41]
	s_barrier
; __device__ __forceinline__ int crow(int r, int hi) { return (r & 3) + 8 * (r >> 2) + 4 * hi; }
; __device__ __forceinline__ int crow(int r, int hi) { return (r & 3) + 8 * (r >> 2) + 4 * hi; }
; __device__ __forceinline__ void qkt(f32x16& p0, f32x16& p1, const char* Ks, const bf16x8* qr, int r32, int hi) {
;   p0 = f32x16{}; p1 = f32x16{};
; #pragma unroll
;   for (int d0 = 0; d0 < 8; ++d0) { int cb = (d0 * 16 + hi * 8) * 2;
;     bf16x8 b0 = *reinterpret_cast<const bf16x8*>(Ks + KSWZ(r32, cb));
;     bf16x8 b1 = *reinterpret_cast<const bf16x8*>(Ks + KSWZ(32 + r32, cb));
;     p0 = __builtin_amdgcn_mfma_f32_32x32x16_bf16(b0, qr[d0], p0, 0, 0, 0);
;     p1 = __builtin_amdgcn_mfma_f32_32x32x16_bf16(b1, qr[d0], p1, 0, 0, 0); }
; __device__ __forceinline__ void attn_sample_unit(int b, int h, int split, const bf16* __restrict__ Q, const float* __restrict__ cache_k, const float* __restrict__ cache_v, ...
;     ...
;       asm volatile("" : "+v"(Qw));
; #pragma unroll
;       for (int d0 = 0; d0 < 8; ++d0) { bf16x8 v = *reinterpret_cast<const bf16x8*>(Qw + d0 * 16); if (r32 >= 16) v = (bf16x8){0, 0, 0, 0, 0, 0, 0, 0}; qr[d0] = v; }
;       qkt(p0, p1, bb + c * 16384, qr, r32, hi);
;       const int kbase = (j == 32) ? 4096 : split * 2048 + j * 64;
;       if (kbase >= 3904) {
;         const float* lp = lut + (kbase - (4096 + r32) + 192);
; #pragma unroll
;         for (int r = 0; r < 16; ++r) { p0[r] += lp[crow(r, hi)]; p1[r] += lp[32 + crow(r, hi)]; }
;       }
.LBB0_357:
	v_mov_b32_e32 v68, v208
	v_mov_b32_e32 v69, v209
	v_mov_b32_e32 v70, v210
	v_mov_b32_e32 v71, v211
	v_mov_b32_e32 v122, v212
	v_mov_b32_e32 v123, v213
	v_mov_b32_e32 v124, v214
	v_mov_b32_e32 v125, v215
	s_and_b32 s8, s71, 0x10000
	s_add_i32 s77, s8, 0
	s_add_i32 s8, s77, s10
	v_add3_u32 v76, s8, v109, v108
	ds_read_b128 v[72:75], v76
	ds_read_b128 v[84:87], v76 offset:8192
	v_mov_b32_e32 v126, v216
	v_mov_b32_e32 v127, v217
	v_mov_b32_e32 v128, v218
	v_mov_b32_e32 v129, v219
	v_add3_u32 v121, s8, v110, v108
	ds_read_b128 v[134:137], v121
	ds_read_b128 v[138:141], v121 offset:8192
	v_add3_u32 v121, s8, v111, v108
	s_cmp_eq_u32 s71, 0x200000
	s_cselect_b64 vcc, -1, 0
	s_waitcnt vmcnt(0) lgkmcnt(0)
	v_cndmask_b32_e64 v91, v71, 0, s[40:41]
	v_cndmask_b32_e64 v90, v70, 0, s[40:41]
	v_cndmask_b32_e64 v89, v69, 0, s[40:41]
	v_cndmask_b32_e64 v88, v68, 0, s[40:41]
	v_cndmask_b32_e64 v125, v125, 0, s[40:41]
	v_cndmask_b32_e64 v124, v124, 0, s[40:41]
	v_mfma_f32_32x32x16_bf16 v[68:83], v[72:75], v[88:91], 0
	v_cndmask_b32_e64 v123, v123, 0, s[40:41]
	v_cndmask_b32_e64 v122, v122, 0, s[40:41]
	v_cndmask_b32_e64 v129, v129, 0, s[40:41]
	v_cndmask_b32_e64 v128, v128, 0, s[40:41]
	v_cndmask_b32_e64 v127, v127, 0, s[40:41]
	v_cndmask_b32_e64 v126, v126, 0, s[40:41]
	v_mfma_f32_32x32x16_bf16 v[68:83], v[134:137], v[122:125], v[68:83]
	v_mov_b32_e32 v134, v220
	v_mov_b32_e32 v135, v221
	v_mov_b32_e32 v136, v222
	v_mov_b32_e32 v137, v223
	s_waitcnt vmcnt(0) lgkmcnt(0)
	v_cndmask_b32_e64 v137, v137, 0, s[40:41]
	v_mfma_f32_32x32x16_bf16 v[84:99], v[84:87], v[88:91], 0
	v_cndmask_b32_e64 v136, v136, 0, s[40:41]
	v_cndmask_b32_e64 v135, v135, 0, s[40:41]
	v_cndmask_b32_e64 v134, v134, 0, s[40:41]
	v_mfma_f32_32x32x16_bf16 v[84:99], v[138:141], v[122:125], v[84:99]
	ds_read_b128 v[122:125], v121
	ds_read_b128 v[138:141], v121 offset:8192
	v_add3_u32 v121, s8, v112, v108
	s_waitcnt lgkmcnt(1)
	v_mfma_f32_32x32x16_bf16 v[68:83], v[122:125], v[126:129], v[68:83]
	v_mov_b32_e32 v122, v224
	v_mov_b32_e32 v123, v225
	v_mov_b32_e32 v124, v226
	v_mov_b32_e32 v125, v227
	s_waitcnt vmcnt(0) lgkmcnt(0)
	v_cndmask_b32_e64 v125, v125, 0, s[40:41]
	v_mfma_f32_32x32x16_bf16 v[84:99], v[138:141], v[126:129], v[84:99]
	ds_read_b128 v[126:129], v121
	ds_read_b128 v[138:141], v121 offset:8192
	v_add3_u32 v121, s8, v113, v108
	v_cndmask_b32_e64 v124, v124, 0, s[40:41]
	v_cndmask_b32_e64 v123, v123, 0, s[40:41]
	v_cndmask_b32_e64 v122, v122, 0, s[40:41]
	s_waitcnt lgkmcnt(1)
	v_mfma_f32_32x32x16_bf16 v[68:83], v[126:129], v[134:137], v[68:83]
	v_mov_b32_e32 v126, v228
	v_mov_b32_e32 v127, v229
	v_mov_b32_e32 v128, v230
	v_mov_b32_e32 v129, v231
	s_waitcnt vmcnt(0) lgkmcnt(0)
	v_cndmask_b32_e64 v129, v129, 0, s[40:41]
	v_mfma_f32_32x32x16_bf16 v[84:99], v[138:141], v[134:137], v[84:99]
	ds_read_b128 v[134:137], v121
	ds_read_b128 v[138:141], v121 offset:8192
	v_add3_u32 v121, s8, v114, v108
	v_cndmask_b32_e64 v128, v128, 0, s[40:41]
	v_cndmask_b32_e64 v127, v127, 0, s[40:41]
	v_cndmask_b32_e64 v126, v126, 0, s[40:41]
	s_waitcnt lgkmcnt(1)
	v_mfma_f32_32x32x16_bf16 v[68:83], v[134:137], v[122:125], v[68:83]
	v_mov_b32_e32 v134, v232
	v_mov_b32_e32 v135, v233
	v_mov_b32_e32 v136, v234
	v_mov_b32_e32 v137, v235
	s_waitcnt vmcnt(0) lgkmcnt(0)
	v_cndmask_b32_e64 v137, v137, 0, s[40:41]
	v_mfma_f32_32x32x16_bf16 v[84:99], v[138:141], v[122:125], v[84:99]
	ds_read_b128 v[122:125], v121
	ds_read_b128 v[138:141], v121 offset:8192
	v_add3_u32 v121, s8, v115, v108
	v_cndmask_b32_e64 v136, v136, 0, s[40:41]
	v_cndmask_b32_e64 v135, v135, 0, s[40:41]
	v_cndmask_b32_e64 v134, v134, 0, s[40:41]
	s_waitcnt lgkmcnt(1)
	v_mfma_f32_32x32x16_bf16 v[68:83], v[122:125], v[126:129], v[68:83]
	v_mov_b32_e32 v122, v236
	v_mov_b32_e32 v123, v237
	v_mov_b32_e32 v124, v238
	v_mov_b32_e32 v125, v239
	s_waitcnt vmcnt(0) lgkmcnt(0)
	v_cndmask_b32_e64 v125, v125, 0, s[40:41]
	v_mfma_f32_32x32x16_bf16 v[84:99], v[138:141], v[126:129], v[84:99]
	ds_read_b128 v[126:129], v121
	ds_read_b128 v[138:141], v121 offset:8192
	v_add3_u32 v121, s8, v116, v108
	v_cndmask_b32_e64 v124, v124, 0, s[40:41]
	v_cndmask_b32_e64 v123, v123, 0, s[40:41]
	v_cndmask_b32_e64 v122, v122, 0, s[40:41]
	s_and_b64 s[8:9], vcc, exec
	s_cselect_b32 s8, 0x1000, s6
	s_waitcnt lgkmcnt(1)
	v_mfma_f32_32x32x16_bf16 v[68:83], v[126:129], v[134:137], v[68:83]
	s_cmpk_lt_u32 s8, 0xf40
	s_waitcnt lgkmcnt(0)
	v_mfma_f32_32x32x16_bf16 v[84:99], v[138:141], v[134:137], v[84:99]
	ds_read_b128 v[126:129], v121
	ds_read_b128 v[134:137], v121 offset:8192
	s_waitcnt lgkmcnt(1)
	v_mfma_f32_32x32x16_bf16 v[68:83], v[126:129], v[122:125], v[68:83]
	s_waitcnt lgkmcnt(0)
	v_mfma_f32_32x32x16_bf16 v[84:99], v[134:137], v[122:125], v[84:99]
	s_cbranch_scc1 .LBB0_359
	v_sub_u32_e32 v121, s8, v106
	v_lshl_add_u32 v121, v121, 2, s65
	s_movk_i32 s8, 0xc300
	v_add3_u32 v121, v121, v2, s8
	ds_read2_b32 v[122:123], v121 offset1:1
	ds_read2_b32 v[124:125], v121 offset0:2 offset1:3
	ds_read2_b32 v[126:127], v121 offset0:8 offset1:9
	ds_read2_b32 v[128:129], v121 offset0:10 offset1:11
	ds_read2_b32 v[130:131], v121 offset0:16 offset1:17
	ds_read2_b32 v[134:135], v121 offset0:18 offset1:19
	ds_read2_b32 v[136:137], v121 offset0:24 offset1:25
	ds_read2_b32 v[138:139], v121 offset0:26 offset1:27
	ds_read2_b32 v[140:141], v121 offset0:32 offset1:33
	ds_read2_b32 v[142:143], v121 offset0:34 offset1:35
	ds_read2_b32 v[144:145], v121 offset0:40 offset1:41
	ds_read2_b32 v[146:147], v121 offset0:42 offset1:43
	s_waitcnt lgkmcnt(4)
	v_pk_add_f32 v[82:83], v[82:83], v[138:139]
	v_pk_add_f32 v[80:81], v[80:81], v[136:137]
	v_pk_add_f32 v[78:79], v[78:79], v[134:135]
	v_pk_add_f32 v[76:77], v[76:77], v[130:131]
	ds_read2_b32 v[130:131], v121 offset0:48 offset1:49
	ds_read2_b32 v[134:135], v121 offset0:50 offset1:51
	ds_read2_b32 v[136:137], v121 offset0:56 offset1:57
	ds_read2_b32 v[138:139], v121 offset0:58 offset1:59
	v_pk_add_f32 v[74:75], v[74:75], v[128:129]
	v_pk_add_f32 v[72:73], v[72:73], v[126:127]
	v_pk_add_f32 v[70:71], v[70:71], v[124:125]
	v_pk_add_f32 v[68:69], v[68:69], v[122:123]
	s_waitcnt lgkmcnt(0)
	v_pk_add_f32 v[98:99], v[98:99], v[138:139]
	v_pk_add_f32 v[96:97], v[96:97], v[136:137]
	v_pk_add_f32 v[94:95], v[94:95], v[134:135]
	v_pk_add_f32 v[92:93], v[92:93], v[130:131]
	v_pk_add_f32 v[90:91], v[90:91], v[146:147]
	v_pk_add_f32 v[88:89], v[88:89], v[144:145]
	v_pk_add_f32 v[86:87], v[86:87], v[142:143]
	v_pk_add_f32 v[84:85], v[84:85], v[140:141]

; __device__ __forceinline__ int crow(int r, int hi) { return (r & 3) + 8 * (r >> 2) + 4 * hi; }
; __device__ __forceinline__ int crow(int r, int hi) { return (r & 3) + 8 * (r >> 2) + 4 * hi; }
; #define DMA_K(j_, b_) do { const char* kb_ = (const char*)Kh + (size_t)(j_) * (64 * LD * 2); _Pragma("unroll") for (int i = 0; i < 4; ++i) \
;     __builtin_amdgcn_global_load_lds((const unsigned*)(kb_ + kgo[i]), (LAS unsigned*)(K_las + (b_) * 16384 + (4 * a + i) * 1024), 16, 0, 0); } while (0)
; #define DMA_V(j_, b_) do { const char* vb_ = (const char*)Vh + (size_t)(j_) * (64 * LD * 2); _Pragma("unroll") for (int hf = 0; hf < 2; ++hf) _Pragma("unroll") for (int i = 0; i < 4; ++i) \
;     __builtin_amdgcn_global_load_lds((const unsigned*)(vb_ + hf * 256 + vgo[i]), (LAS unsigned*)(V_las + (b_) * 32768 + hf * 16384 + (4 * a + i) * 1024), 16, 0, 0); } while (0)
; __device__ __forceinline__ void attn_unit2(const bf16* __restrict__ Qb, const bf16* __restrict__ Kh, const bf16* __restrict__ Vh, bf16* __restrict__ Ob,
;                                            int NT, int lim, int qrow0, const float* lut, char* lds, float* scr) {
;     ...
;     for (int j = 0; j <= NT; ++j) {
;       if (j + 1 < NT) DMA_K(j + 1, (j + 1) & 1);
;       if (j < NT) DMA_V(j, j & 1);
;       if (j >= 1) {
;         const float* al = al0 + ((j - 1) & 1) * 128;
;         if (__any(al[r32] < 1.f) || __any(al[32 + r32] < 1.f)) {
; #pragma unroll
;           for (int rb = 0; rb < 2; ++rb)
; #pragma unroll
;             for (int d = 0; d < 4; ++d)
; #pragma unroll
;               for (int r = 0; r < 16; ++r) o[rb][d][r] *= al[rb * 32 + crow(r, hi)]; }
.LBB0_433:
	s_and_b32 s14, s10, 1
	s_lshl_b32 s15, s14, 9
	s_add_i32 s15, s4, s15
	v_lshl_add_u32 v177, v172, 2, s15
	ds_read_b32 v200, v177
	s_and_b32 s23, s9, 0x8000
	s_add_i32 s23, s6, s23
	v_lshl_add_u64 v[156:157], v[138:139], 0, s[36:37]
	s_add_i32 m0, s23, 0x8000
	v_lshl_add_u64 v[158:159], v[156:157], 0, s[54:55]
	global_load_lds_dwordx4 v[158:159], off
	v_lshl_add_u64 v[158:159], v[142:143], 0, s[36:37]
	v_lshl_add_u64 v[164:165], v[158:159], 0, s[54:55]
	s_add_i32 m0, s23, 0x8400
	v_lshl_add_u64 v[156:157], v[156:157], 0, s[68:69]
	global_load_lds_dwordx4 v[164:165], off
	v_lshl_add_u64 v[164:165], v[144:145], 0, s[36:37]
	v_lshl_add_u64 v[178:179], v[164:165], 0, s[54:55]
	s_add_i32 m0, s23, 0x8800
	s_nop 0
	global_load_lds_dwordx4 v[178:179], off
	v_lshl_add_u64 v[178:179], v[146:147], 0, s[36:37]
	v_lshl_add_u64 v[180:181], v[178:179], 0, s[54:55]
	s_add_i32 m0, s23, 0x8c00
	s_nop 0
	global_load_lds_dwordx4 v[180:181], off
	v_lshl_add_u64 v[158:159], v[158:159], 0, s[68:69]
	v_lshl_add_u64 v[164:165], v[164:165], 0, s[68:69]
	v_lshl_add_u64 v[252:253], v[178:179], 0, s[68:69]
	s_waitcnt lgkmcnt(0)
	v_cmp_gt_f32_e32 vcc, 1.0, v200
	s_cmp_lg_u64 vcc, 0
	s_cselect_b64 s[46:47], -1, 0
	s_cbranch_vccz .LBB0_438
	s_andn2_b64 vcc, exec, s[46:47]
	s_cbranch_vccnz .LBB0_436
.LBB0_435:
	v_add_u32_e32 v201, s15, v140
	ds_read_b128 v[178:181], v201
	ds_read_b128 v[182:185], v201 offset:32
	ds_read_b128 v[186:189], v201 offset:64
	ds_read_b128 v[190:193], v201 offset:96
	s_waitcnt lgkmcnt(0)
	v_pk_mul_f32 v[118:119], v[118:119], v[180:181]
	v_pk_mul_f32 v[120:121], v[120:121], v[182:183]
	v_pk_mul_f32 v[124:125], v[124:125], v[186:187]
	v_pk_mul_f32 v[128:129], v[128:129], v[190:191]
	v_pk_mul_f32 v[130:131], v[130:131], v[192:193]
	v_pk_mul_f32 v[126:127], v[126:127], v[188:189]
	v_pk_mul_f32 v[122:123], v[122:123], v[184:185]
	v_pk_mul_f32 v[116:117], v[116:117], v[178:179]
	v_pk_mul_f32 v[112:113], v[112:113], v[190:191]
	v_pk_mul_f32 v[108:109], v[108:109], v[186:187]
	v_pk_mul_f32 v[104:105], v[104:105], v[182:183]
	v_pk_mul_f32 v[114:115], v[114:115], v[192:193]
	v_pk_mul_f32 v[110:111], v[110:111], v[188:189]
	v_pk_mul_f32 v[106:107], v[106:107], v[184:185]
	v_pk_mul_f32 v[102:103], v[102:103], v[180:181]
	v_pk_mul_f32 v[100:101], v[100:101], v[178:179]
	v_pk_mul_f32 v[96:97], v[96:97], v[190:191]
	v_pk_mul_f32 v[92:93], v[92:93], v[186:187]
	v_pk_mul_f32 v[88:89], v[88:89], v[182:183]
	v_pk_mul_f32 v[98:99], v[98:99], v[192:193]
	v_pk_mul_f32 v[94:95], v[94:95], v[188:189]
	v_pk_mul_f32 v[90:91], v[90:91], v[184:185]
	v_pk_mul_f32 v[86:87], v[86:87], v[180:181]
	v_pk_mul_f32 v[84:85], v[84:85], v[178:179]
	v_pk_mul_f32 v[80:81], v[80:81], v[190:191]
	v_pk_mul_f32 v[76:77], v[76:77], v[186:187]
	v_pk_mul_f32 v[72:73], v[72:73], v[182:183]
	v_pk_mul_f32 v[82:83], v[82:83], v[192:193]
	v_pk_mul_f32 v[78:79], v[78:79], v[188:189]
	v_pk_mul_f32 v[74:75], v[74:75], v[184:185]
	v_pk_mul_f32 v[70:71], v[70:71], v[180:181]
	v_pk_mul_f32 v[68:69], v[68:69], v[178:179]
	ds_read_b128 v[178:181], v201 offset:128
	ds_read_b128 v[182:185], v201 offset:160
	ds_read_b128 v[186:189], v201 offset:192
	ds_read_b128 v[190:193], v201 offset:224
	s_waitcnt lgkmcnt(0)
	v_pk_mul_f32 v[54:55], v[54:55], v[180:181]
	v_pk_mul_f32 v[56:57], v[56:57], v[182:183]
	v_pk_mul_f32 v[60:61], v[60:61], v[186:187]
	v_pk_mul_f32 v[64:65], v[64:65], v[190:191]
	v_pk_mul_f32 v[66:67], v[66:67], v[192:193]
	v_pk_mul_f32 v[62:63], v[62:63], v[188:189]
	v_pk_mul_f32 v[58:59], v[58:59], v[184:185]
	v_pk_mul_f32 v[52:53], v[52:53], v[178:179]
	v_pk_mul_f32 v[48:49], v[48:49], v[190:191]
	v_pk_mul_f32 v[44:45], v[44:45], v[186:187]
	v_pk_mul_f32 v[40:41], v[40:41], v[182:183]
	v_pk_mul_f32 v[50:51], v[50:51], v[192:193]
	v_pk_mul_f32 v[46:47], v[46:47], v[188:189]
	v_pk_mul_f32 v[42:43], v[42:43], v[184:185]
	v_pk_mul_f32 v[38:39], v[38:39], v[180:181]
	v_pk_mul_f32 v[36:37], v[36:37], v[178:179]
	v_pk_mul_f32 v[32:33], v[32:33], v[190:191]
	v_pk_mul_f32 v[28:29], v[28:29], v[186:187]
	v_pk_mul_f32 v[24:25], v[24:25], v[182:183]
	v_pk_mul_f32 v[34:35], v[34:35], v[192:193]
	v_pk_mul_f32 v[30:31], v[30:31], v[188:189]
	v_pk_mul_f32 v[26:27], v[26:27], v[184:185]
	v_pk_mul_f32 v[22:23], v[22:23], v[180:181]
	v_pk_mul_f32 v[20:21], v[20:21], v[178:179]
	v_pk_mul_f32 v[16:17], v[16:17], v[190:191]
	v_pk_mul_f32 v[12:13], v[12:13], v[186:187]
	v_pk_mul_f32 v[8:9], v[8:9], v[182:183]
	v_pk_mul_f32 v[18:19], v[18:19], v[192:193]
	v_pk_mul_f32 v[14:15], v[14:15], v[188:189]
	v_pk_mul_f32 v[10:11], v[10:11], v[184:185]
	v_pk_mul_f32 v[6:7], v[6:7], v[180:181]
	v_pk_mul_f32 v[4:5], v[4:5], v[178:179]
; #define SBAR() __builtin_amdgcn_sched_barrier(0)
; #define VRD(D0, L) const s16x4 L##0 = tr_read<v_rd_off(D0, 0, 0)>(vb), L##1 = tr_read<v_rd_off(D0, 0, 1)>(vb), L##2 = tr_read<v_rd_off(D0, 1, 0)>(vb), L##3 = tr_read<v_rd_off(D0, 1, 1)>(vb), \
;                          L##4 = tr_read<v_rd_off(D0, 2, 0)>(vb), L##5 = tr_read<v_rd_off(D0, 2, 1)>(vb), L##6 = tr_read<v_rd_off(D0, 3, 0)>(vb), L##7 = tr_read<v_rd_off(D0, 3, 1)>(vb)
; __device__ __forceinline__ void pv_four(f32x16 (&o)[2][4], int vb, bf16x8 pa0, bf16x8 pa1, bf16x8 pa2, bf16x8 pa3, bf16x8 pb0, bf16x8 pb1, bf16x8 pb2, bf16x8 pb3) {
;     ...
;   VRD(0, x); SBAR();
;   VRD(1, y); asm volatile("s_waitcnt lgkmcnt(8)" ::: "memory"); SBAR(); MMA(0, x); SBAR();
;   VRD(2, z); asm volatile("s_waitcnt lgkmcnt(8)" ::: "memory"); SBAR(); MMA(1, y); SBAR();
;   VRD(3, w); asm volatile("s_waitcnt lgkmcnt(8)" ::: "memory"); SBAR(); MMA(2, z); SBAR();
;   asm volatile("s_waitcnt lgkmcnt(0)" ::: "memory"); SBAR(); MMA(3, w);
;     ...
; }
; __device__ __forceinline__ void attn_unit2(const bf16* __restrict__ Qb, const bf16* __restrict__ Kh, const bf16* __restrict__ Vh, bf16* __restrict__ Ob,
;                                            int NT, int lim, int qrow0, const float* lut, char* lds, float* scr) {
;     ...
;         const char* ps = P0 + ((j - 1) & 1) * 16384 + lane * 16;
;         const bf16x8 pa0 = *(const bf16x8*)(ps), pa1 = *(const bf16x8*)(ps + 1024), pa2 = *(const bf16x8*)(ps + 2048), pa3 = *(const bf16x8*)(ps + 3072);
;         const bf16x8 pb0 = *(const bf16x8*)(ps + 4096), pb1 = *(const bf16x8*)(ps + 4096 + 1024), pb2 = *(const bf16x8*)(ps + 4096 + 2048), pb3 = *(const bf16x8*)(ps + 4096 + 3072);
;         const int vb = vrb + ((j - 1) & 1) * 32768 + ch * 16384;
;         pv_four(o, vb, pa0, pa1, pa2, pa3, pb0, pb1, pb2, pb3);
;       }
;       asm volatile("s_waitcnt vmcnt(0)" ::: "memory");
;       __syncthreads();
.LBB0_436:
	v_lshl_add_u32 v201, s14, 14, v175
	ds_read_b128 v[178:181], v201
	ds_read_b128 v[182:185], v201 offset:1024
	ds_read_b128 v[186:189], v201 offset:2048
	ds_read_b128 v[190:193], v201 offset:3072
	ds_read_b128 v[194:197], v201 offset:4096
	ds_read_b128 v[208:211], v201 offset:5120
	ds_read_b128 v[212:215], v201 offset:6144
	ds_read_b128 v[216:219], v201 offset:7168
	v_lshl_add_u32 v207, s14, 15, v176
	ds_read_b64_tr_b16 v[220:221], v207 offset:0
	ds_read_b64_tr_b16 v[222:223], v207 offset:0x800
	ds_read_b64_tr_b16 v[224:225], v207 offset:0x1000
	ds_read_b64_tr_b16 v[226:227], v207 offset:0x1800
	ds_read_b64_tr_b16 v[228:229], v207 offset:0x2000
	ds_read_b64_tr_b16 v[230:231], v207 offset:0x2800
	ds_read_b64_tr_b16 v[232:233], v207 offset:0x3000
	ds_read_b64_tr_b16 v[234:235], v207 offset:0x3800
	ds_read_b64_tr_b16 v[236:237], v207 offset:0x200
	ds_read_b64_tr_b16 v[238:239], v207 offset:0xa00
	ds_read_b64_tr_b16 v[240:241], v207 offset:0x1200
	ds_read_b64_tr_b16 v[242:243], v207 offset:0x1a00
	ds_read_b64_tr_b16 v[244:245], v207 offset:0x2200
	ds_read_b64_tr_b16 v[246:247], v207 offset:0x2a00
	ds_read_b64_tr_b16 v[248:249], v207 offset:0x3200
	ds_read_b64_tr_b16 v[250:251], v207 offset:0x3a00
	s_add_i32 m0, s23, 0xc000
	s_nop 0
	global_load_lds_dwordx4 v[156:157], off
	s_add_i32 m0, s23, 0xc400
	s_nop 0
	global_load_lds_dwordx4 v[158:159], off
	s_add_i32 m0, s23, 0xc800
	s_nop 0
	global_load_lds_dwordx4 v[164:165], off
	s_add_i32 m0, s23, 0xcc00
	s_nop 0
	global_load_lds_dwordx4 v[252:253], off
	s_waitcnt lgkmcnt(8)
	s_waitcnt lgkmcnt(0)
	v_mfma_f32_32x32x16_bf16 v[116:131], v[178:181], v[220:223], v[116:131]
	v_mfma_f32_32x32x16_bf16 v[52:67], v[194:197], v[220:223], v[52:67]
	v_mfma_f32_32x32x16_bf16 v[116:131], v[182:185], v[224:227], v[116:131]
	v_mfma_f32_32x32x16_bf16 v[52:67], v[208:211], v[224:227], v[52:67]
	v_mfma_f32_32x32x16_bf16 v[116:131], v[186:189], v[228:231], v[116:131]
	v_mfma_f32_32x32x16_bf16 v[52:67], v[212:215], v[228:231], v[52:67]
	v_mfma_f32_32x32x16_bf16 v[116:131], v[190:193], v[232:235], v[116:131]
	v_mfma_f32_32x32x16_bf16 v[52:67], v[216:219], v[232:235], v[52:67]
	ds_read_b64_tr_b16 v[220:221], v207 offset:0x400
	ds_read_b64_tr_b16 v[222:223], v207 offset:0xc00
	ds_read_b64_tr_b16 v[224:225], v207 offset:0x1400
	ds_read_b64_tr_b16 v[226:227], v207 offset:0x1c00
	ds_read_b64_tr_b16 v[228:229], v207 offset:0x2400
	ds_read_b64_tr_b16 v[230:231], v207 offset:0x2c00
	ds_read_b64_tr_b16 v[232:233], v207 offset:0x3400
	ds_read_b64_tr_b16 v[234:235], v207 offset:0x3c00
	s_waitcnt lgkmcnt(8)
	v_mfma_f32_32x32x16_bf16 v[100:115], v[178:181], v[236:239], v[100:115]
	v_mfma_f32_32x32x16_bf16 v[36:51], v[194:197], v[236:239], v[36:51]
	v_mfma_f32_32x32x16_bf16 v[100:115], v[182:185], v[240:243], v[100:115]
	v_mfma_f32_32x32x16_bf16 v[36:51], v[208:211], v[240:243], v[36:51]
	v_mfma_f32_32x32x16_bf16 v[100:115], v[186:189], v[244:247], v[100:115]
	v_mfma_f32_32x32x16_bf16 v[36:51], v[212:215], v[244:247], v[36:51]
	v_mfma_f32_32x32x16_bf16 v[100:115], v[190:193], v[248:251], v[100:115]
	v_mfma_f32_32x32x16_bf16 v[36:51], v[216:219], v[248:251], v[36:51]
	ds_read_b64_tr_b16 v[236:237], v207 offset:0x600
	ds_read_b64_tr_b16 v[238:239], v207 offset:0xe00
	ds_read_b64_tr_b16 v[240:241], v207 offset:0x1600
	ds_read_b64_tr_b16 v[242:243], v207 offset:0x1e00
	ds_read_b64_tr_b16 v[244:245], v207 offset:0x2600
	ds_read_b64_tr_b16 v[246:247], v207 offset:0x2e00
	ds_read_b64_tr_b16 v[248:249], v207 offset:0x3600
	ds_read_b64_tr_b16 v[250:251], v207 offset:0x3e00
	s_waitcnt lgkmcnt(8)
	v_mfma_f32_32x32x16_bf16 v[84:99], v[178:181], v[220:223], v[84:99]
	v_mfma_f32_32x32x16_bf16 v[20:35], v[194:197], v[220:223], v[20:35]
	v_mfma_f32_32x32x16_bf16 v[84:99], v[182:185], v[224:227], v[84:99]
	v_mfma_f32_32x32x16_bf16 v[20:35], v[208:211], v[224:227], v[20:35]
	v_mfma_f32_32x32x16_bf16 v[84:99], v[186:189], v[228:231], v[84:99]
	v_mfma_f32_32x32x16_bf16 v[20:35], v[212:215], v[228:231], v[20:35]
	v_mfma_f32_32x32x16_bf16 v[84:99], v[190:193], v[232:235], v[84:99]
	v_mfma_f32_32x32x16_bf16 v[20:35], v[216:219], v[232:235], v[20:35]
	s_waitcnt lgkmcnt(0)
	v_mfma_f32_32x32x16_bf16 v[68:83], v[178:181], v[236:239], v[68:83]
	s_add_i32 s9, s9, 0x8000
	s_waitcnt vmcnt(0)
	s_add_u32 s36, s36, 0x40000
	s_addc_u32 s37, s37, 0
	s_add_i32 s14, s10, 1
	s_addk_i32 s7, 0x4000
	s_cmp_eq_u32 s8, s36
	v_mfma_f32_32x32x16_bf16 v[4:19], v[194:197], v[236:239], v[4:19]
	s_waitcnt vmcnt(0)
	s_barrier
	v_mfma_f32_32x32x16_bf16 v[68:83], v[182:185], v[240:243], v[68:83]
	v_mfma_f32_32x32x16_bf16 v[4:19], v[208:211], v[240:243], v[4:19]
	v_mfma_f32_32x32x16_bf16 v[68:83], v[186:189], v[244:247], v[68:83]
	v_mfma_f32_32x32x16_bf16 v[4:19], v[212:215], v[244:247], v[4:19]
	v_mfma_f32_32x32x16_bf16 v[68:83], v[190:193], v[248:251], v[68:83]
	v_mfma_f32_32x32x16_bf16 v[4:19], v[216:219], v[248:251], v[4:19]
	s_cbranch_scc1 .LBB0_439
	s_mov_b32 s10, s14
	s_cmp_lt_u32 s10, s5
	s_cselect_b64 s[38:39], -1, 0
	s_cmp_ge_u32 s10, s5
	s_cbranch_scc0 .LBB0_432
	s_branch .LBB0_433
.LBB0_438:
	ds_read_b32 v200, v177 offset:128
	s_waitcnt lgkmcnt(0)
	v_cmp_gt_f32_e32 vcc, 1.0, v200
	s_cmp_lg_u64 vcc, 0
	s_cselect_b64 s[46:47], -1, 0
	s_andn2_b64 vcc, exec, s[46:47]
	s_cbranch_vccz .LBB0_435
	s_branch .LBB0_436

; __device__ __forceinline__ int crow(int r, int hi) { return (r & 3) + 8 * (r >> 2) + 4 * hi; }
; __device__ __forceinline__ int crow(int r, int hi) { return (r & 3) + 8 * (r >> 2) + 4 * hi; }
; __device__ __forceinline__ void qkt(f32x16& p0, f32x16& p1, const char* Ks, const bf16x8* qr, int r32, int hi) {
;   p0 = f32x16{}; p1 = f32x16{};
; #pragma unroll
;   for (int d0 = 0; d0 < 8; ++d0) { int cb = (d0 * 16 + hi * 8) * 2;
;     bf16x8 b0 = *reinterpret_cast<const bf16x8*>(Ks + KSWZ(r32, cb));
;     bf16x8 b1 = *reinterpret_cast<const bf16x8*>(Ks + KSWZ(32 + r32, cb));
;     p0 = __builtin_amdgcn_mfma_f32_32x32x16_bf16(b0, qr[d0], p0, 0, 0, 0);
;     p1 = __builtin_amdgcn_mfma_f32_32x32x16_bf16(b1, qr[d0], p1, 0, 0, 0); }
; __device__ __forceinline__ void fix_prompt(f32x16& p0, f32x16& p1, int jt, int lim, int qrow0, int r32, int hi, const float* lut) {
;   if (jt > lim) {
; #pragma unroll
;     for (int r = 0; r < 16; ++r) { p0[r] = -1e30f; p1[r] = -1e30f; }
;   } else if (64 * jt >= qrow0 - 153) {
;     const float* lp = lut + (64 * jt - (qrow0 + r32) + 192);
; #pragma unroll
;     for (int r = 0; r < 16; ++r) { p0[r] += lp[crow(r, hi)]; p1[r] += lp[32 + crow(r, hi)]; }
;   }
; }
.LBB0_447:
	s_setprio 3
	s_and_b32 s14, s10, 1
	s_lshl_b32 s15, s14, 14
	s_add_i32 s23, s15, 0
	v_add3_u32 v81, s23, v70, v69
	ds_read_b128 v[82:85], v81
	ds_read_b128 v[208:211], v81 offset:8192
	v_add3_u32 v81, s23, v71, v69
	ds_read_b128 v[212:215], v81
	ds_read_b128 v[216:219], v81 offset:8192
	v_add3_u32 v81, s23, v72, v69
	ds_read_b128 v[220:223], v81
	ds_read_b128 v[224:227], v81 offset:8192
	v_add3_u32 v81, s23, v73, v69
	ds_read_b128 v[228:231], v81
	ds_read_b128 v[232:235], v81 offset:8192
	v_add3_u32 v81, s23, v74, v69
	ds_read_b128 v[236:239], v81
	ds_read_b128 v[240:243], v81 offset:8192
	v_add3_u32 v81, s23, v75, v69
	ds_read_b128 v[244:247], v81
	ds_read_b128 v[248:251], v81 offset:8192
	s_cmp_gt_u32 s10, s5
	s_waitcnt vmcnt(7) lgkmcnt(11)
	v_mfma_f32_32x32x16_bf16 v[4:19], v[82:85], v[36:39], 0
	s_waitcnt lgkmcnt(10)
	v_mfma_f32_32x32x16_bf16 v[20:35], v[208:211], v[36:39], 0
	v_add3_u32 v81, s23, v76, v69
	ds_read_b128 v[132:135], v81
	ds_read_b128 v[136:139], v81 offset:8192
	s_waitcnt vmcnt(6) lgkmcnt(11)
	v_mfma_f32_32x32x16_bf16 v[4:19], v[212:215], v[40:43], v[4:19]
	s_waitcnt lgkmcnt(10)
	v_mfma_f32_32x32x16_bf16 v[20:35], v[216:219], v[40:43], v[20:35]
	v_add3_u32 v81, s23, v77, v69
	ds_read_b128 v[140:143], v81
	ds_read_b128 v[144:147], v81 offset:8192
	s_waitcnt vmcnt(5) lgkmcnt(11)
	v_mfma_f32_32x32x16_bf16 v[4:19], v[220:223], v[44:47], v[4:19]
	s_waitcnt lgkmcnt(10)
	v_mfma_f32_32x32x16_bf16 v[20:35], v[224:227], v[44:47], v[20:35]
	s_waitcnt vmcnt(4) lgkmcnt(9)
	v_mfma_f32_32x32x16_bf16 v[4:19], v[228:231], v[48:51], v[4:19]
	s_waitcnt lgkmcnt(8)
	v_mfma_f32_32x32x16_bf16 v[20:35], v[232:235], v[48:51], v[20:35]
	s_waitcnt vmcnt(3) lgkmcnt(7)
	v_mfma_f32_32x32x16_bf16 v[4:19], v[236:239], v[52:55], v[4:19]
	s_waitcnt lgkmcnt(6)
	v_mfma_f32_32x32x16_bf16 v[20:35], v[240:243], v[52:55], v[20:35]
	s_waitcnt vmcnt(2) lgkmcnt(5)
	v_mfma_f32_32x32x16_bf16 v[4:19], v[244:247], v[56:59], v[4:19]
	s_waitcnt lgkmcnt(4)
	v_mfma_f32_32x32x16_bf16 v[20:35], v[248:251], v[56:59], v[20:35]
	s_waitcnt vmcnt(1) lgkmcnt(3)
	v_mfma_f32_32x32x16_bf16 v[4:19], v[132:135], v[60:63], v[4:19]
	s_waitcnt lgkmcnt(2)
	v_mfma_f32_32x32x16_bf16 v[20:35], v[136:139], v[60:63], v[20:35]
	s_waitcnt vmcnt(0) lgkmcnt(1)
	v_mfma_f32_32x32x16_bf16 v[4:19], v[140:143], v[64:67], v[4:19]
	s_waitcnt lgkmcnt(0)
	v_mfma_f32_32x32x16_bf16 v[20:35], v[144:147], v[64:67], v[20:35]
	s_cbranch_scc1 .LBB0_450
	s_cmp_lt_i32 s9, s6
	s_cbranch_scc1 .LBB0_451
	v_add_u32_e32 v81, s8, v78
	v_add_u32_e32 v82, 0x20500, v81
	v_add_u32_e32 v84, 0x20580, v81
	ds_read2_b32 v[82:83], v82 offset1:1
	ds_read2_b32 v[84:85], v84 offset1:1
	v_add_u32_e32 v86, 0x20588, v81
	v_add_u32_e32 v88, 0x205a0, v81
	v_add_u32_e32 v90, 0x205a8, v81
	v_add_u32_e32 v92, 0x205c0, v81
	s_waitcnt lgkmcnt(0)
	v_pk_add_f32 v[20:21], v[20:21], v[84:85]
	v_add_u32_e32 v84, 0x20508, v81
	ds_read2_b32 v[84:85], v84 offset1:1
	ds_read2_b32 v[86:87], v86 offset1:1
	v_add_u32_e32 v94, 0x205c8, v81
	v_add_u32_e32 v96, 0x205e0, v81
	v_add_u32_e32 v98, 0x20568, v81
	s_waitcnt lgkmcnt(1)
	v_pk_add_f32 v[6:7], v[6:7], v[84:85]
	s_waitcnt lgkmcnt(0)
	v_pk_add_f32 v[22:23], v[22:23], v[86:87]
	v_add_u32_e32 v86, 0x20520, v81
	ds_read2_b32 v[86:87], v86 offset1:1
	ds_read2_b32 v[88:89], v88 offset1:1
	v_pk_add_f32 v[4:5], v[4:5], v[82:83]
	s_waitcnt lgkmcnt(1)
	v_pk_add_f32 v[8:9], v[8:9], v[86:87]
	s_waitcnt lgkmcnt(0)
	v_pk_add_f32 v[24:25], v[24:25], v[88:89]
	v_add_u32_e32 v88, 0x20528, v81
	ds_read2_b32 v[88:89], v88 offset1:1
	ds_read2_b32 v[90:91], v90 offset1:1
	s_waitcnt lgkmcnt(1)
	v_pk_add_f32 v[10:11], v[10:11], v[88:89]
	s_waitcnt lgkmcnt(0)
	v_pk_add_f32 v[26:27], v[26:27], v[90:91]
	v_add_u32_e32 v90, 0x20540, v81
	ds_read2_b32 v[90:91], v90 offset1:1
	ds_read2_b32 v[92:93], v92 offset1:1
	s_waitcnt lgkmcnt(1)
	v_pk_add_f32 v[12:13], v[12:13], v[90:91]
	s_waitcnt lgkmcnt(0)
	v_pk_add_f32 v[28:29], v[28:29], v[92:93]
	v_add_u32_e32 v92, 0x20548, v81
	ds_read2_b32 v[92:93], v92 offset1:1
	ds_read2_b32 v[94:95], v94 offset1:1
	s_waitcnt lgkmcnt(1)
	v_pk_add_f32 v[14:15], v[14:15], v[92:93]
	s_waitcnt lgkmcnt(0)
	v_pk_add_f32 v[30:31], v[30:31], v[94:95]
	v_add_u32_e32 v94, 0x20560, v81
	ds_read2_b32 v[94:95], v94 offset1:1
	ds_read2_b32 v[96:97], v96 offset1:1
	v_add_u32_e32 v81, 0x205e8, v81
	ds_read2_b32 v[98:99], v98 offset1:1
	s_waitcnt lgkmcnt(2)
	v_pk_add_f32 v[16:17], v[16:17], v[94:95]
	s_waitcnt lgkmcnt(1)
	v_pk_add_f32 v[32:33], v[32:33], v[96:97]
	ds_read2_b32 v[96:97], v81 offset1:1
	s_waitcnt lgkmcnt(1)
	v_pk_add_f32 v[18:19], v[18:19], v[98:99]
	s_waitcnt lgkmcnt(0)
	v_add_f32_e32 v34, v34, v96
	v_add_f32_e32 v35, v35, v97
	s_branch .LBB0_451
.LBB0_450:
	s_nop 8
	v_mov_b32_e32 v4, 0xf149f2ca
	v_mov_b32_e32 v5, v4
	v_mov_b32_e32 v6, v4
	v_mov_b32_e32 v7, v4
	v_mov_b32_e32 v8, v4
	v_mov_b32_e32 v9, v4
	v_mov_b32_e32 v10, v4
	v_mov_b32_e32 v11, v4
	v_mov_b32_e32 v12, v4
	v_mov_b32_e32 v13, v4
	v_mov_b32_e32 v14, v4
	v_mov_b32_e32 v15, v4
	v_mov_b32_e32 v16, v4
	v_mov_b32_e32 v17, v4
	v_mov_b32_e32 v18, v4
	v_mov_b32_e32 v19, v4
	v_mov_b32_e32 v20, v4
	v_mov_b32_e32 v21, v4
	v_mov_b32_e32 v22, v4
	v_mov_b32_e32 v23, v4
	v_mov_b32_e32 v24, v4
	v_mov_b32_e32 v25, v4
	v_mov_b32_e32 v26, v4
	v_mov_b32_e32 v27, v4
	v_mov_b32_e32 v28, v4
	v_mov_b32_e32 v29, v4
	v_mov_b32_e32 v30, v4
	v_mov_b32_e32 v31, v4
	v_mov_b32_e32 v32, v4
	v_mov_b32_e32 v33, v4
	v_mov_b32_e32 v34, v4
	v_mov_b32_e32 v35, v4
